# K-loop LDS-DMA loads use the SGPR-base (saddr) form: 16 v_lshl_add_u64 address VALU per iteration removed, per-tile combined row-offset VGPRs
# speedup vs baseline: 1.0162x; 1.0026x over previous
.Lprio_done:
	s_add_u32 s0, s90, 0x80
	s_addc_u32 s1, s91, 0
	s_add_u32 s11, s2, 0x100
	s_addc_u32 s24, s3, 0
	s_mov_b32 s2, 0
	s_add_i32 s90, s2, 2
	s_add_u32 s82, s0, 0x80
	s_addc_u32 s3, s1, 0
	s_add_i32 s83, 0, 0x10000
	s_cmp_eq_u32 s62, s2
	s_cselect_b32 s3, s23, s3
	s_cselect_b32 s2, s22, s82
	s_cselect_b32 vcc_hi, s13, s24
	s_cselect_b32 vcc_lo, s12, s11
	s_add_i32 s82, 0, 0x14000
	v_add_u32_e32 v140, s83, v157
	v_add_u32_e32 v144, s82, v157
	v_add_u32_e32 v232, s26, v150
	v_add_u32_e32 v233, s26, v154
	v_add_u32_e32 v234, s58, v148
	v_add_u32_e32 v235, s58, v152
	ds_read_b128 v[128:131], v140
	ds_read_b128 v[132:135], v140 offset:1024
	ds_read_b128 v[136:139], v140 offset:2048
	ds_read_b128 v[140:143], v140 offset:3072
	ds_read_b128 v[166:169], v144
	ds_read_b128 v[176:179], v144 offset:1024
	ds_read_b128 v[180:183], v144 offset:2048
	ds_read_b128 v[184:187], v144 offset:3072
	s_add_i32 m0, s37, 0xc000
	ds_read_b128 v[188:191], v242
	ds_read_b128 v[192:195], v242 offset:1024
	ds_read_b128 v[196:199], v242 offset:2048
	ds_read_b128 v[200:203], v242 offset:3072
	ds_read_b128 v[204:207], v242 offset:4096
	ds_read_b128 v[208:211], v242 offset:5120
	ds_read_b128 v[212:215], v242 offset:6144
	ds_read_b128 v[216:219], v242 offset:7168
	global_load_lds_dwordx4 v160, s[0:1]
	s_add_i32 m0, s37, 0xe000
	s_nop 0
	global_load_lds_dwordx4 v162, s[0:1]
	s_waitcnt vmcnt(8) lgkmcnt(0)
	s_barrier
	v_mfma_f32_16x16x32_bf16 v[124:127], v[128:131], v[188:191], 0
	v_mfma_f32_16x16x32_bf16 v[120:123], v[136:139], v[188:191], 0
	v_mfma_f32_16x16x32_bf16 v[108:111], v[128:131], v[196:199], 0
	v_mfma_f32_16x16x32_bf16 v[104:107], v[136:139], v[196:199], 0
	v_mfma_f32_16x16x32_bf16 v[92:95], v[128:131], v[204:207], 0
	v_mfma_f32_16x16x32_bf16 v[88:91], v[136:139], v[204:207], 0
	v_mfma_f32_16x16x32_bf16 v[76:79], v[128:131], v[212:215], 0
	v_mfma_f32_16x16x32_bf16 v[72:75], v[136:139], v[212:215], 0
	v_mfma_f32_16x16x32_bf16 v[124:127], v[132:135], v[192:195], v[124:127]
	v_mfma_f32_16x16x32_bf16 v[120:123], v[140:143], v[192:195], v[120:123]
	v_mfma_f32_16x16x32_bf16 v[108:111], v[132:135], v[200:203], v[108:111]
	v_mfma_f32_16x16x32_bf16 v[104:107], v[140:143], v[200:203], v[104:107]
	v_mfma_f32_16x16x32_bf16 v[92:95], v[132:135], v[208:211], v[92:95]
	v_mfma_f32_16x16x32_bf16 v[88:91], v[140:143], v[208:211], v[88:91]
	v_mfma_f32_16x16x32_bf16 v[76:79], v[132:135], v[216:219], v[76:79]
	v_mfma_f32_16x16x32_bf16 v[72:75], v[140:143], v[216:219], v[72:75]
	v_mfma_f32_16x16x32_bf16 v[116:119], v[166:169], v[188:191], 0
	v_mfma_f32_16x16x32_bf16 v[112:115], v[180:183], v[188:191], 0
	v_mfma_f32_16x16x32_bf16 v[100:103], v[166:169], v[196:199], 0
	v_mfma_f32_16x16x32_bf16 v[96:99], v[180:183], v[196:199], 0
	v_mfma_f32_16x16x32_bf16 v[84:87], v[166:169], v[204:207], 0
	v_mfma_f32_16x16x32_bf16 v[80:83], v[180:183], v[204:207], 0
	v_mfma_f32_16x16x32_bf16 v[68:71], v[166:169], v[212:215], 0
	v_mfma_f32_16x16x32_bf16 v[64:67], v[180:183], v[212:215], 0
	v_mfma_f32_16x16x32_bf16 v[116:119], v[176:179], v[192:195], v[116:119]
	v_mfma_f32_16x16x32_bf16 v[112:115], v[184:187], v[192:195], v[112:115]
	v_mfma_f32_16x16x32_bf16 v[100:103], v[176:179], v[200:203], v[100:103]
	v_mfma_f32_16x16x32_bf16 v[96:99], v[184:187], v[200:203], v[96:99]
	v_mfma_f32_16x16x32_bf16 v[84:87], v[176:179], v[208:211], v[84:87]
	v_mfma_f32_16x16x32_bf16 v[80:83], v[184:187], v[208:211], v[80:83]
	v_mfma_f32_16x16x32_bf16 v[68:71], v[176:179], v[216:219], v[68:71]
	v_mfma_f32_16x16x32_bf16 v[64:67], v[184:187], v[216:219], v[64:67]
	s_barrier
	s_add_i32 s83, s83, s36
	s_mov_b32 m0, s83
	ds_read_b128 v[188:191], v242 offset:16384
	ds_read_b128 v[192:195], v242 offset:17408
	ds_read_b128 v[196:199], v242 offset:18432
	ds_read_b128 v[200:203], v242 offset:19456
	ds_read_b128 v[204:207], v242 offset:20480
	ds_read_b128 v[208:211], v242 offset:21504
	ds_read_b128 v[212:215], v242 offset:22528
	ds_read_b128 v[216:219], v242 offset:23552
	global_load_lds_dwordx4 v150, vcc
	s_add_i32 m0, s83, 0x2000
	s_add_i32 s82, s82, s36
	global_load_lds_dwordx4 v154, vcc
	s_mov_b32 m0, s82
	s_nop 0
	global_load_lds_dwordx4 v232, vcc
	s_add_i32 m0, s82, 0x2000
	s_nop 0
	global_load_lds_dwordx4 v233, vcc
	s_mov_b32 m0, s37
	s_nop 0
	global_load_lds_dwordx4 v148, s[2:3]
	s_mov_b32 m0, s42
	s_nop 0
	global_load_lds_dwordx4 v152, s[2:3]
	s_waitcnt vmcnt(8) lgkmcnt(0)
	s_barrier
	v_mfma_f32_16x16x32_bf16 v[60:63], v[128:131], v[188:191], 0
	v_mfma_f32_16x16x32_bf16 v[56:59], v[136:139], v[188:191], 0
	v_mfma_f32_16x16x32_bf16 v[44:47], v[128:131], v[196:199], 0
	v_mfma_f32_16x16x32_bf16 v[40:43], v[136:139], v[196:199], 0
	v_mfma_f32_16x16x32_bf16 v[28:31], v[128:131], v[204:207], 0
	v_mfma_f32_16x16x32_bf16 v[24:27], v[136:139], v[204:207], 0
	v_mfma_f32_16x16x32_bf16 v[12:15], v[128:131], v[212:215], 0
	v_mfma_f32_16x16x32_bf16 v[8:11], v[136:139], v[212:215], 0
	v_mfma_f32_16x16x32_bf16 v[60:63], v[132:135], v[192:195], v[60:63]
	v_mfma_f32_16x16x32_bf16 v[56:59], v[140:143], v[192:195], v[56:59]
	v_mfma_f32_16x16x32_bf16 v[44:47], v[132:135], v[200:203], v[44:47]
	v_mfma_f32_16x16x32_bf16 v[40:43], v[140:143], v[200:203], v[40:43]
	v_mfma_f32_16x16x32_bf16 v[28:31], v[132:135], v[208:211], v[28:31]
	v_mfma_f32_16x16x32_bf16 v[24:27], v[140:143], v[208:211], v[24:27]
	v_mfma_f32_16x16x32_bf16 v[12:15], v[132:135], v[216:219], v[12:15]
	v_mfma_f32_16x16x32_bf16 v[8:11], v[140:143], v[216:219], v[8:11]
	v_mfma_f32_16x16x32_bf16 v[52:55], v[166:169], v[188:191], 0
	v_mfma_f32_16x16x32_bf16 v[48:51], v[180:183], v[188:191], 0
	v_mfma_f32_16x16x32_bf16 v[36:39], v[166:169], v[196:199], 0
	v_mfma_f32_16x16x32_bf16 v[32:35], v[180:183], v[196:199], 0
	v_mfma_f32_16x16x32_bf16 v[20:23], v[166:169], v[204:207], 0
	v_mfma_f32_16x16x32_bf16 v[16:19], v[180:183], v[204:207], 0
	v_mfma_f32_16x16x32_bf16 v[4:7], v[166:169], v[212:215], 0
	v_mfma_f32_16x16x32_bf16 v[0:3], v[180:183], v[212:215], 0
	v_mfma_f32_16x16x32_bf16 v[52:55], v[176:179], v[192:195], v[52:55]
	v_mfma_f32_16x16x32_bf16 v[48:51], v[184:187], v[192:195], v[48:51]
	v_mfma_f32_16x16x32_bf16 v[36:39], v[176:179], v[200:203], v[36:39]
	v_mfma_f32_16x16x32_bf16 v[32:35], v[184:187], v[200:203], v[32:35]
	v_mfma_f32_16x16x32_bf16 v[20:23], v[176:179], v[208:211], v[20:23]
	v_mfma_f32_16x16x32_bf16 v[16:19], v[184:187], v[208:211], v[16:19]
	v_mfma_f32_16x16x32_bf16 v[4:7], v[176:179], v[216:219], v[4:7]
	v_mfma_f32_16x16x32_bf16 v[0:3], v[184:187], v[216:219], v[0:3]
	s_barrier
	s_add_i32 s82, 0, 0x18000
	s_add_i32 s83, 0, 0x1c000
	v_add_u32_e32 v140, s82, v157
	v_add_u32_e32 v144, s83, v157
	ds_read_b128 v[128:131], v140
	ds_read_b128 v[132:135], v140 offset:1024
	ds_read_b128 v[136:139], v140 offset:2048
	ds_read_b128 v[140:143], v140 offset:3072
	ds_read_b128 v[166:169], v144
	ds_read_b128 v[176:179], v144 offset:1024
	ds_read_b128 v[180:183], v144 offset:2048
	ds_read_b128 v[184:187], v144 offset:3072
	s_mov_b32 m0, s43
	ds_read_b128 v[188:191], v242 offset:32768
	ds_read_b128 v[192:195], v242 offset:33792
	ds_read_b128 v[196:199], v242 offset:34816
	ds_read_b128 v[200:203], v242 offset:35840
	ds_read_b128 v[204:207], v242 offset:36864
	ds_read_b128 v[208:211], v242 offset:37888
	ds_read_b128 v[212:215], v242 offset:38912
	ds_read_b128 v[216:219], v242 offset:39936
	global_load_lds_dwordx4 v234, s[2:3]
	s_mov_b32 m0, s16
	s_nop 0
	global_load_lds_dwordx4 v235, s[2:3]
	s_waitcnt vmcnt(8) lgkmcnt(0)
	s_barrier
	v_mfma_f32_16x16x32_bf16 v[124:127], v[128:131], v[188:191], v[124:127]
	v_mfma_f32_16x16x32_bf16 v[120:123], v[136:139], v[188:191], v[120:123]
	v_mfma_f32_16x16x32_bf16 v[108:111], v[128:131], v[196:199], v[108:111]
	v_mfma_f32_16x16x32_bf16 v[104:107], v[136:139], v[196:199], v[104:107]
	v_mfma_f32_16x16x32_bf16 v[92:95], v[128:131], v[204:207], v[92:95]
	v_mfma_f32_16x16x32_bf16 v[88:91], v[136:139], v[204:207], v[88:91]
	v_mfma_f32_16x16x32_bf16 v[76:79], v[128:131], v[212:215], v[76:79]
	v_mfma_f32_16x16x32_bf16 v[72:75], v[136:139], v[212:215], v[72:75]
	v_mfma_f32_16x16x32_bf16 v[124:127], v[132:135], v[192:195], v[124:127]
	v_mfma_f32_16x16x32_bf16 v[120:123], v[140:143], v[192:195], v[120:123]
	v_mfma_f32_16x16x32_bf16 v[108:111], v[132:135], v[200:203], v[108:111]
	v_mfma_f32_16x16x32_bf16 v[104:107], v[140:143], v[200:203], v[104:107]
	v_mfma_f32_16x16x32_bf16 v[92:95], v[132:135], v[208:211], v[92:95]
	v_mfma_f32_16x16x32_bf16 v[88:91], v[140:143], v[208:211], v[88:91]
	v_mfma_f32_16x16x32_bf16 v[76:79], v[132:135], v[216:219], v[76:79]
	v_mfma_f32_16x16x32_bf16 v[72:75], v[140:143], v[216:219], v[72:75]
	v_mfma_f32_16x16x32_bf16 v[116:119], v[166:169], v[188:191], v[116:119]
	v_mfma_f32_16x16x32_bf16 v[112:115], v[180:183], v[188:191], v[112:115]
	v_mfma_f32_16x16x32_bf16 v[100:103], v[166:169], v[196:199], v[100:103]
	v_mfma_f32_16x16x32_bf16 v[96:99], v[180:183], v[196:199], v[96:99]
	v_mfma_f32_16x16x32_bf16 v[84:87], v[166:169], v[204:207], v[84:87]
	v_mfma_f32_16x16x32_bf16 v[80:83], v[180:183], v[204:207], v[80:83]
	v_mfma_f32_16x16x32_bf16 v[68:71], v[166:169], v[212:215], v[68:71]
	v_mfma_f32_16x16x32_bf16 v[64:67], v[180:183], v[212:215], v[64:67]
	v_mfma_f32_16x16x32_bf16 v[116:119], v[176:179], v[192:195], v[116:119]
	v_mfma_f32_16x16x32_bf16 v[112:115], v[184:187], v[192:195], v[112:115]
	v_mfma_f32_16x16x32_bf16 v[100:103], v[176:179], v[200:203], v[100:103]
	v_mfma_f32_16x16x32_bf16 v[96:99], v[184:187], v[200:203], v[96:99]
	v_mfma_f32_16x16x32_bf16 v[84:87], v[176:179], v[208:211], v[84:87]
	v_mfma_f32_16x16x32_bf16 v[80:83], v[184:187], v[208:211], v[80:83]
	v_mfma_f32_16x16x32_bf16 v[68:71], v[176:179], v[216:219], v[68:71]
	v_mfma_f32_16x16x32_bf16 v[64:67], v[184:187], v[216:219], v[64:67]
	s_barrier
	s_add_u32 vcc_lo, vcc_lo, 0x80
	s_addc_u32 vcc_hi, vcc_hi, 0
	s_add_u32 s2, s2, 0x80
	s_addc_u32 s3, s3, 0
	s_add_i32 m0, s82, s36
	ds_read_b128 v[188:191], v242 offset:49152
	ds_read_b128 v[192:195], v242 offset:50176
	ds_read_b128 v[196:199], v242 offset:51200
	ds_read_b128 v[200:203], v242 offset:52224
	ds_read_b128 v[204:207], v242 offset:53248
	ds_read_b128 v[208:211], v242 offset:54272
	ds_read_b128 v[212:215], v242 offset:55296
	ds_read_b128 v[216:219], v242 offset:56320
	global_load_lds_dwordx4 v150, vcc
	s_add_i32 m0, m0, 0x2000
	s_nop 0
	global_load_lds_dwordx4 v154, vcc
	s_add_i32 m0, s83, s36
	s_nop 0
	global_load_lds_dwordx4 v232, vcc
	s_add_i32 m0, m0, 0x2000
	s_nop 0
	global_load_lds_dwordx4 v233, vcc
	s_mov_b32 m0, s63
	s_nop 0
	global_load_lds_dwordx4 v148, s[2:3]
	s_mov_b32 m0, s18
	s_nop 0
	global_load_lds_dwordx4 v152, s[2:3]
	s_waitcnt vmcnt(8) lgkmcnt(0)
	s_barrier
	v_mfma_f32_16x16x32_bf16 v[60:63], v[128:131], v[188:191], v[60:63]
	v_mfma_f32_16x16x32_bf16 v[56:59], v[136:139], v[188:191], v[56:59]
	v_mfma_f32_16x16x32_bf16 v[44:47], v[128:131], v[196:199], v[44:47]
	v_mfma_f32_16x16x32_bf16 v[40:43], v[136:139], v[196:199], v[40:43]
	v_mfma_f32_16x16x32_bf16 v[28:31], v[128:131], v[204:207], v[28:31]
	v_mfma_f32_16x16x32_bf16 v[24:27], v[136:139], v[204:207], v[24:27]
	v_mfma_f32_16x16x32_bf16 v[12:15], v[128:131], v[212:215], v[12:15]
	v_mfma_f32_16x16x32_bf16 v[8:11], v[136:139], v[212:215], v[8:11]
	v_mfma_f32_16x16x32_bf16 v[60:63], v[132:135], v[192:195], v[60:63]
	v_mfma_f32_16x16x32_bf16 v[56:59], v[140:143], v[192:195], v[56:59]
	v_mfma_f32_16x16x32_bf16 v[44:47], v[132:135], v[200:203], v[44:47]
	v_mfma_f32_16x16x32_bf16 v[40:43], v[140:143], v[200:203], v[40:43]
	v_mfma_f32_16x16x32_bf16 v[28:31], v[132:135], v[208:211], v[28:31]
	v_mfma_f32_16x16x32_bf16 v[24:27], v[140:143], v[208:211], v[24:27]
	v_mfma_f32_16x16x32_bf16 v[12:15], v[132:135], v[216:219], v[12:15]
	v_mfma_f32_16x16x32_bf16 v[8:11], v[140:143], v[216:219], v[8:11]
	v_mfma_f32_16x16x32_bf16 v[52:55], v[166:169], v[188:191], v[52:55]
	v_mfma_f32_16x16x32_bf16 v[48:51], v[180:183], v[188:191], v[48:51]
	v_mfma_f32_16x16x32_bf16 v[36:39], v[166:169], v[196:199], v[36:39]
	v_mfma_f32_16x16x32_bf16 v[32:35], v[180:183], v[196:199], v[32:35]
	v_mfma_f32_16x16x32_bf16 v[20:23], v[166:169], v[204:207], v[20:23]
	v_mfma_f32_16x16x32_bf16 v[16:19], v[180:183], v[204:207], v[16:19]
	v_mfma_f32_16x16x32_bf16 v[4:7], v[166:169], v[212:215], v[4:7]
	v_mfma_f32_16x16x32_bf16 v[0:3], v[180:183], v[212:215], v[0:3]
	v_mfma_f32_16x16x32_bf16 v[52:55], v[176:179], v[192:195], v[52:55]
	v_mfma_f32_16x16x32_bf16 v[48:51], v[184:187], v[192:195], v[48:51]
	v_mfma_f32_16x16x32_bf16 v[36:39], v[176:179], v[200:203], v[36:39]
	v_mfma_f32_16x16x32_bf16 v[32:35], v[184:187], v[200:203], v[32:35]
	v_mfma_f32_16x16x32_bf16 v[20:23], v[176:179], v[208:211], v[20:23]
	v_mfma_f32_16x16x32_bf16 v[16:19], v[184:187], v[208:211], v[16:19]
	v_mfma_f32_16x16x32_bf16 v[4:7], v[176:179], v[216:219], v[4:7]
	v_mfma_f32_16x16x32_bf16 v[0:3], v[184:187], v[216:219], v[0:3]
	s_barrier
	s_add_u32 s0, s0, 0x100
	s_addc_u32 s1, s1, 0
	s_add_u32 s11, s11, 0x100
	s_addc_u32 s24, s24, 0
	s_cmp_ge_u32 s90, s60
	s_mov_b32 s2, s90
	s_cbranch_scc1 .LBB0_297
.LBB0_295:
	s_add_i32 s90, s2, 2
	s_add_u32 s82, s0, 0x80
	s_addc_u32 s3, s1, 0
	s_add_i32 s83, 0, 0x10000
	s_cmp_eq_u32 s62, s2
	s_cselect_b32 s3, s23, s3
	s_cselect_b32 s2, s22, s82
	s_cselect_b32 vcc_hi, s13, s24
	s_cselect_b32 vcc_lo, s12, s11
	s_add_i32 s82, 0, 0x14000
	v_add_u32_e32 v140, s83, v157
	v_add_u32_e32 v144, s82, v157
	ds_read_b128 v[128:131], v140
	ds_read_b128 v[132:135], v140 offset:1024
	ds_read_b128 v[136:139], v140 offset:2048
	ds_read_b128 v[140:143], v140 offset:3072
	ds_read_b128 v[166:169], v144
	ds_read_b128 v[176:179], v144 offset:1024
	ds_read_b128 v[180:183], v144 offset:2048
	ds_read_b128 v[184:187], v144 offset:3072
	s_add_i32 m0, s37, 0xc000
	ds_read_b128 v[188:191], v242
	ds_read_b128 v[192:195], v242 offset:1024
	ds_read_b128 v[196:199], v242 offset:2048
	ds_read_b128 v[200:203], v242 offset:3072
	ds_read_b128 v[204:207], v242 offset:4096
	ds_read_b128 v[208:211], v242 offset:5120
	ds_read_b128 v[212:215], v242 offset:6144
	ds_read_b128 v[216:219], v242 offset:7168
	global_load_lds_dwordx4 v160, s[0:1]
	s_add_i32 m0, s37, 0xe000
	s_nop 0
	global_load_lds_dwordx4 v162, s[0:1]
	s_waitcnt vmcnt(8) lgkmcnt(0)
	s_barrier
	v_mfma_f32_16x16x32_bf16 v[124:127], v[128:131], v[188:191], v[124:127]
	v_mfma_f32_16x16x32_bf16 v[120:123], v[136:139], v[188:191], v[120:123]
	v_mfma_f32_16x16x32_bf16 v[108:111], v[128:131], v[196:199], v[108:111]
	v_mfma_f32_16x16x32_bf16 v[104:107], v[136:139], v[196:199], v[104:107]
	v_mfma_f32_16x16x32_bf16 v[92:95], v[128:131], v[204:207], v[92:95]
	v_mfma_f32_16x16x32_bf16 v[88:91], v[136:139], v[204:207], v[88:91]
	v_mfma_f32_16x16x32_bf16 v[76:79], v[128:131], v[212:215], v[76:79]
	v_mfma_f32_16x16x32_bf16 v[72:75], v[136:139], v[212:215], v[72:75]
	v_mfma_f32_16x16x32_bf16 v[124:127], v[132:135], v[192:195], v[124:127]
	v_mfma_f32_16x16x32_bf16 v[120:123], v[140:143], v[192:195], v[120:123]
	v_mfma_f32_16x16x32_bf16 v[108:111], v[132:135], v[200:203], v[108:111]
	v_mfma_f32_16x16x32_bf16 v[104:107], v[140:143], v[200:203], v[104:107]
	v_mfma_f32_16x16x32_bf16 v[92:95], v[132:135], v[208:211], v[92:95]
	v_mfma_f32_16x16x32_bf16 v[88:91], v[140:143], v[208:211], v[88:91]
	v_mfma_f32_16x16x32_bf16 v[76:79], v[132:135], v[216:219], v[76:79]
	v_mfma_f32_16x16x32_bf16 v[72:75], v[140:143], v[216:219], v[72:75]
	v_mfma_f32_16x16x32_bf16 v[116:119], v[166:169], v[188:191], v[116:119]
	v_mfma_f32_16x16x32_bf16 v[112:115], v[180:183], v[188:191], v[112:115]
	v_mfma_f32_16x16x32_bf16 v[100:103], v[166:169], v[196:199], v[100:103]
	v_mfma_f32_16x16x32_bf16 v[96:99], v[180:183], v[196:199], v[96:99]
	v_mfma_f32_16x16x32_bf16 v[84:87], v[166:169], v[204:207], v[84:87]
	v_mfma_f32_16x16x32_bf16 v[80:83], v[180:183], v[204:207], v[80:83]
	v_mfma_f32_16x16x32_bf16 v[68:71], v[166:169], v[212:215], v[68:71]
	v_mfma_f32_16x16x32_bf16 v[64:67], v[180:183], v[212:215], v[64:67]
	v_mfma_f32_16x16x32_bf16 v[116:119], v[176:179], v[192:195], v[116:119]
	v_mfma_f32_16x16x32_bf16 v[112:115], v[184:187], v[192:195], v[112:115]
	v_mfma_f32_16x16x32_bf16 v[100:103], v[176:179], v[200:203], v[100:103]
	v_mfma_f32_16x16x32_bf16 v[96:99], v[184:187], v[200:203], v[96:99]
	v_mfma_f32_16x16x32_bf16 v[84:87], v[176:179], v[208:211], v[84:87]
	v_mfma_f32_16x16x32_bf16 v[80:83], v[184:187], v[208:211], v[80:83]
	v_mfma_f32_16x16x32_bf16 v[68:71], v[176:179], v[216:219], v[68:71]
	v_mfma_f32_16x16x32_bf16 v[64:67], v[184:187], v[216:219], v[64:67]
	s_barrier
	s_add_i32 s83, s83, s36
	s_mov_b32 m0, s83
	ds_read_b128 v[188:191], v242 offset:16384
	ds_read_b128 v[192:195], v242 offset:17408
	ds_read_b128 v[196:199], v242 offset:18432
	ds_read_b128 v[200:203], v242 offset:19456
	ds_read_b128 v[204:207], v242 offset:20480
	ds_read_b128 v[208:211], v242 offset:21504
	ds_read_b128 v[212:215], v242 offset:22528
	ds_read_b128 v[216:219], v242 offset:23552
	global_load_lds_dwordx4 v150, vcc
	s_add_i32 m0, s83, 0x2000
	s_add_i32 s82, s82, s36
	global_load_lds_dwordx4 v154, vcc
	s_mov_b32 m0, s82
	s_nop 0
	global_load_lds_dwordx4 v232, vcc
	s_add_i32 m0, s82, 0x2000
	s_nop 0
	global_load_lds_dwordx4 v233, vcc
	s_mov_b32 m0, s37
	s_nop 0
	global_load_lds_dwordx4 v148, s[2:3]
	s_mov_b32 m0, s42
	s_nop 0
	global_load_lds_dwordx4 v152, s[2:3]
	s_waitcnt vmcnt(8) lgkmcnt(0)
	s_barrier
	v_mfma_f32_16x16x32_bf16 v[60:63], v[128:131], v[188:191], v[60:63]
	v_mfma_f32_16x16x32_bf16 v[56:59], v[136:139], v[188:191], v[56:59]
	v_mfma_f32_16x16x32_bf16 v[44:47], v[128:131], v[196:199], v[44:47]
	v_mfma_f32_16x16x32_bf16 v[40:43], v[136:139], v[196:199], v[40:43]
	v_mfma_f32_16x16x32_bf16 v[28:31], v[128:131], v[204:207], v[28:31]
	v_mfma_f32_16x16x32_bf16 v[24:27], v[136:139], v[204:207], v[24:27]
	v_mfma_f32_16x16x32_bf16 v[12:15], v[128:131], v[212:215], v[12:15]
	v_mfma_f32_16x16x32_bf16 v[8:11], v[136:139], v[212:215], v[8:11]
	v_mfma_f32_16x16x32_bf16 v[60:63], v[132:135], v[192:195], v[60:63]
	v_mfma_f32_16x16x32_bf16 v[56:59], v[140:143], v[192:195], v[56:59]
	v_mfma_f32_16x16x32_bf16 v[44:47], v[132:135], v[200:203], v[44:47]
	v_mfma_f32_16x16x32_bf16 v[40:43], v[140:143], v[200:203], v[40:43]
	v_mfma_f32_16x16x32_bf16 v[28:31], v[132:135], v[208:211], v[28:31]
	v_mfma_f32_16x16x32_bf16 v[24:27], v[140:143], v[208:211], v[24:27]
	v_mfma_f32_16x16x32_bf16 v[12:15], v[132:135], v[216:219], v[12:15]
	v_mfma_f32_16x16x32_bf16 v[8:11], v[140:143], v[216:219], v[8:11]
	v_mfma_f32_16x16x32_bf16 v[52:55], v[166:169], v[188:191], v[52:55]
	v_mfma_f32_16x16x32_bf16 v[48:51], v[180:183], v[188:191], v[48:51]
	v_mfma_f32_16x16x32_bf16 v[36:39], v[166:169], v[196:199], v[36:39]
	v_mfma_f32_16x16x32_bf16 v[32:35], v[180:183], v[196:199], v[32:35]
	v_mfma_f32_16x16x32_bf16 v[20:23], v[166:169], v[204:207], v[20:23]
	v_mfma_f32_16x16x32_bf16 v[16:19], v[180:183], v[204:207], v[16:19]
	v_mfma_f32_16x16x32_bf16 v[4:7], v[166:169], v[212:215], v[4:7]
	v_mfma_f32_16x16x32_bf16 v[0:3], v[180:183], v[212:215], v[0:3]
	v_mfma_f32_16x16x32_bf16 v[52:55], v[176:179], v[192:195], v[52:55]
	v_mfma_f32_16x16x32_bf16 v[48:51], v[184:187], v[192:195], v[48:51]
	v_mfma_f32_16x16x32_bf16 v[36:39], v[176:179], v[200:203], v[36:39]
	v_mfma_f32_16x16x32_bf16 v[32:35], v[184:187], v[200:203], v[32:35]
	v_mfma_f32_16x16x32_bf16 v[20:23], v[176:179], v[208:211], v[20:23]
	v_mfma_f32_16x16x32_bf16 v[16:19], v[184:187], v[208:211], v[16:19]
	v_mfma_f32_16x16x32_bf16 v[4:7], v[176:179], v[216:219], v[4:7]
	v_mfma_f32_16x16x32_bf16 v[0:3], v[184:187], v[216:219], v[0:3]
	s_barrier
	s_add_i32 s82, 0, 0x18000
	s_add_i32 s83, 0, 0x1c000
	v_add_u32_e32 v140, s82, v157
	v_add_u32_e32 v144, s83, v157
	ds_read_b128 v[128:131], v140
	ds_read_b128 v[132:135], v140 offset:1024
	ds_read_b128 v[136:139], v140 offset:2048
	ds_read_b128 v[140:143], v140 offset:3072
	ds_read_b128 v[166:169], v144
	ds_read_b128 v[176:179], v144 offset:1024
	ds_read_b128 v[180:183], v144 offset:2048
	ds_read_b128 v[184:187], v144 offset:3072
	s_mov_b32 m0, s43
	ds_read_b128 v[188:191], v242 offset:32768
	ds_read_b128 v[192:195], v242 offset:33792
	ds_read_b128 v[196:199], v242 offset:34816
	ds_read_b128 v[200:203], v242 offset:35840
	ds_read_b128 v[204:207], v242 offset:36864
	ds_read_b128 v[208:211], v242 offset:37888
	ds_read_b128 v[212:215], v242 offset:38912
	ds_read_b128 v[216:219], v242 offset:39936
	global_load_lds_dwordx4 v234, s[2:3]
	s_mov_b32 m0, s16
	s_nop 0
	global_load_lds_dwordx4 v235, s[2:3]
	s_waitcnt vmcnt(8) lgkmcnt(0)
	s_barrier
	v_mfma_f32_16x16x32_bf16 v[124:127], v[128:131], v[188:191], v[124:127]
	v_mfma_f32_16x16x32_bf16 v[120:123], v[136:139], v[188:191], v[120:123]
	v_mfma_f32_16x16x32_bf16 v[108:111], v[128:131], v[196:199], v[108:111]
	v_mfma_f32_16x16x32_bf16 v[104:107], v[136:139], v[196:199], v[104:107]
	v_mfma_f32_16x16x32_bf16 v[92:95], v[128:131], v[204:207], v[92:95]
	v_mfma_f32_16x16x32_bf16 v[88:91], v[136:139], v[204:207], v[88:91]
	v_mfma_f32_16x16x32_bf16 v[76:79], v[128:131], v[212:215], v[76:79]
	v_mfma_f32_16x16x32_bf16 v[72:75], v[136:139], v[212:215], v[72:75]
	v_mfma_f32_16x16x32_bf16 v[124:127], v[132:135], v[192:195], v[124:127]
	v_mfma_f32_16x16x32_bf16 v[120:123], v[140:143], v[192:195], v[120:123]
	v_mfma_f32_16x16x32_bf16 v[108:111], v[132:135], v[200:203], v[108:111]
	v_mfma_f32_16x16x32_bf16 v[104:107], v[140:143], v[200:203], v[104:107]
	v_mfma_f32_16x16x32_bf16 v[92:95], v[132:135], v[208:211], v[92:95]
	v_mfma_f32_16x16x32_bf16 v[88:91], v[140:143], v[208:211], v[88:91]
	v_mfma_f32_16x16x32_bf16 v[76:79], v[132:135], v[216:219], v[76:79]
	v_mfma_f32_16x16x32_bf16 v[72:75], v[140:143], v[216:219], v[72:75]
	v_mfma_f32_16x16x32_bf16 v[116:119], v[166:169], v[188:191], v[116:119]
	v_mfma_f32_16x16x32_bf16 v[112:115], v[180:183], v[188:191], v[112:115]
	v_mfma_f32_16x16x32_bf16 v[100:103], v[166:169], v[196:199], v[100:103]
	v_mfma_f32_16x16x32_bf16 v[96:99], v[180:183], v[196:199], v[96:99]
	v_mfma_f32_16x16x32_bf16 v[84:87], v[166:169], v[204:207], v[84:87]
	v_mfma_f32_16x16x32_bf16 v[80:83], v[180:183], v[204:207], v[80:83]
	v_mfma_f32_16x16x32_bf16 v[68:71], v[166:169], v[212:215], v[68:71]
	v_mfma_f32_16x16x32_bf16 v[64:67], v[180:183], v[212:215], v[64:67]
	v_mfma_f32_16x16x32_bf16 v[116:119], v[176:179], v[192:195], v[116:119]
	v_mfma_f32_16x16x32_bf16 v[112:115], v[184:187], v[192:195], v[112:115]
	v_mfma_f32_16x16x32_bf16 v[100:103], v[176:179], v[200:203], v[100:103]
	v_mfma_f32_16x16x32_bf16 v[96:99], v[184:187], v[200:203], v[96:99]
	v_mfma_f32_16x16x32_bf16 v[84:87], v[176:179], v[208:211], v[84:87]
	v_mfma_f32_16x16x32_bf16 v[80:83], v[184:187], v[208:211], v[80:83]
	v_mfma_f32_16x16x32_bf16 v[68:71], v[176:179], v[216:219], v[68:71]
	v_mfma_f32_16x16x32_bf16 v[64:67], v[184:187], v[216:219], v[64:67]
	s_barrier
	s_add_u32 vcc_lo, vcc_lo, 0x80
	s_addc_u32 vcc_hi, vcc_hi, 0
	s_add_u32 s2, s2, 0x80
	s_addc_u32 s3, s3, 0
	s_add_i32 m0, s82, s36
	ds_read_b128 v[188:191], v242 offset:49152
	ds_read_b128 v[192:195], v242 offset:50176
	ds_read_b128 v[196:199], v242 offset:51200
	ds_read_b128 v[200:203], v242 offset:52224
	ds_read_b128 v[204:207], v242 offset:53248
	ds_read_b128 v[208:211], v242 offset:54272
	ds_read_b128 v[212:215], v242 offset:55296
	ds_read_b128 v[216:219], v242 offset:56320
	global_load_lds_dwordx4 v150, vcc
	s_add_i32 m0, m0, 0x2000
	s_nop 0
	global_load_lds_dwordx4 v154, vcc
	s_add_i32 m0, s83, s36
	s_nop 0
	global_load_lds_dwordx4 v232, vcc
	s_add_i32 m0, m0, 0x2000
	s_nop 0
	global_load_lds_dwordx4 v233, vcc
	s_mov_b32 m0, s63
	s_nop 0
	global_load_lds_dwordx4 v148, s[2:3]
	s_mov_b32 m0, s18
	s_nop 0
	global_load_lds_dwordx4 v152, s[2:3]
	s_waitcnt vmcnt(8) lgkmcnt(0)
	s_barrier
	v_mfma_f32_16x16x32_bf16 v[60:63], v[128:131], v[188:191], v[60:63]
	v_mfma_f32_16x16x32_bf16 v[56:59], v[136:139], v[188:191], v[56:59]
	v_mfma_f32_16x16x32_bf16 v[44:47], v[128:131], v[196:199], v[44:47]
	v_mfma_f32_16x16x32_bf16 v[40:43], v[136:139], v[196:199], v[40:43]
	v_mfma_f32_16x16x32_bf16 v[28:31], v[128:131], v[204:207], v[28:31]
	v_mfma_f32_16x16x32_bf16 v[24:27], v[136:139], v[204:207], v[24:27]
	v_mfma_f32_16x16x32_bf16 v[12:15], v[128:131], v[212:215], v[12:15]
	v_mfma_f32_16x16x32_bf16 v[8:11], v[136:139], v[212:215], v[8:11]
	v_mfma_f32_16x16x32_bf16 v[60:63], v[132:135], v[192:195], v[60:63]
	v_mfma_f32_16x16x32_bf16 v[56:59], v[140:143], v[192:195], v[56:59]
	v_mfma_f32_16x16x32_bf16 v[44:47], v[132:135], v[200:203], v[44:47]
	v_mfma_f32_16x16x32_bf16 v[40:43], v[140:143], v[200:203], v[40:43]
	v_mfma_f32_16x16x32_bf16 v[28:31], v[132:135], v[208:211], v[28:31]
	v_mfma_f32_16x16x32_bf16 v[24:27], v[140:143], v[208:211], v[24:27]
	v_mfma_f32_16x16x32_bf16 v[12:15], v[132:135], v[216:219], v[12:15]
	v_mfma_f32_16x16x32_bf16 v[8:11], v[140:143], v[216:219], v[8:11]
	v_mfma_f32_16x16x32_bf16 v[52:55], v[166:169], v[188:191], v[52:55]
	v_mfma_f32_16x16x32_bf16 v[48:51], v[180:183], v[188:191], v[48:51]
	v_mfma_f32_16x16x32_bf16 v[36:39], v[166:169], v[196:199], v[36:39]
	v_mfma_f32_16x16x32_bf16 v[32:35], v[180:183], v[196:199], v[32:35]
	v_mfma_f32_16x16x32_bf16 v[20:23], v[166:169], v[204:207], v[20:23]
	v_mfma_f32_16x16x32_bf16 v[16:19], v[180:183], v[204:207], v[16:19]
	v_mfma_f32_16x16x32_bf16 v[4:7], v[166:169], v[212:215], v[4:7]
	v_mfma_f32_16x16x32_bf16 v[0:3], v[180:183], v[212:215], v[0:3]
	v_mfma_f32_16x16x32_bf16 v[52:55], v[176:179], v[192:195], v[52:55]
	v_mfma_f32_16x16x32_bf16 v[48:51], v[184:187], v[192:195], v[48:51]
	v_mfma_f32_16x16x32_bf16 v[36:39], v[176:179], v[200:203], v[36:39]
	v_mfma_f32_16x16x32_bf16 v[32:35], v[184:187], v[200:203], v[32:35]
	v_mfma_f32_16x16x32_bf16 v[20:23], v[176:179], v[208:211], v[20:23]
	v_mfma_f32_16x16x32_bf16 v[16:19], v[184:187], v[208:211], v[16:19]
	v_mfma_f32_16x16x32_bf16 v[4:7], v[176:179], v[216:219], v[4:7]
	v_mfma_f32_16x16x32_bf16 v[0:3], v[184:187], v[216:219], v[0:3]
	s_barrier
	s_add_u32 s0, s0, 0x100
	s_addc_u32 s1, s1, 0
	s_add_u32 s11, s11, 0x100
	s_addc_u32 s24, s24, 0
	s_cmp_ge_u32 s90, s60
	s_mov_b32 s2, s90
	s_cbranch_scc0 .LBB0_295
	s_branch .LBB0_297
